# attention combine (map-0 waves): sub-LN gain loads issued together with one wait; output leaves through an LDS row tile as 8 full-line dwordx4 stores per wave instead of 16 dwordx2 stores of 32-byte p
# speedup vs baseline: 1.0191x; 1.0191x over previous
.LBB0_1137:
	s_waitcnt lgkmcnt(0)
	s_barrier
	s_andn2_b64 vcc, exec, s[16:17]
	s_cbranch_vccnz .LBB0_1115
	v_div_scale_f32 v3, s[0:1], v2, v2, 1.0
	v_rcp_f32_e32 v84, v3
	v_div_scale_f32 v86, vcc, 1.0, v2, 1.0
	s_lshl_b32 s50, s90, 9
	v_fma_f32 v87, -v3, v84, 1.0
	v_fmac_f32_e32 v84, v87, v84
	v_mul_f32_e32 v90, v86, v84
	v_fma_f32 v87, -v3, v90, v86
	v_fmac_f32_e32 v90, v87, v84
	v_fma_f32 v3, -v3, v90, v86
	ds_read_b128 v[86:89], v152
	v_div_fmas_f32 v3, v3, v84, v90
	ds_read_b128 v[90:93], v152 offset:1024
	v_div_fixup_f32 v84, v3, v2, 1.0
	v_mov_b32_e32 v145, v0
	s_waitcnt lgkmcnt(0)
	v_xor_b32_e32 v3, 0x80000000, v89
	v_xor_b32_e32 v2, 0x80000000, v88
	v_pk_fma_f32 v[80:81], v[80:81], v[84:85], v[86:87] op_sel_hi:[1,0,1] neg_lo:[0,0,1] neg_hi:[0,0,1]
	v_pk_fma_f32 v[82:83], v[82:83], v[84:85], v[2:3] op_sel_hi:[1,0,1]
	v_pk_mul_f32 v[86:87], v[80:81], v[80:81]
	v_pk_mul_f32 v[2:3], v[82:83], v[82:83]
	s_nop 0
	v_pk_mov_b32 v[88:89], v[86:87], v[2:3] op_sel:[1,0]
	v_mov_b32_e32 v87, v3
	v_pk_fma_f32 v[2:3], v[76:77], v[84:85], v[90:91] op_sel_hi:[1,0,1] neg_lo:[0,0,1] neg_hi:[0,0,1]
	v_xor_b32_e32 v77, 0x80000000, v93
	v_xor_b32_e32 v76, 0x80000000, v92
	v_pk_fma_f32 v[76:77], v[78:79], v[84:85], v[76:77] op_sel_hi:[1,0,1]
	v_pk_mul_f32 v[90:91], v[2:3], v[2:3]
	v_pk_mul_f32 v[78:79], v[76:77], v[76:77]
	v_pk_add_f32 v[94:95], v[88:89], v[86:87]
	v_pk_mov_b32 v[92:93], v[90:91], v[78:79] op_sel:[1,0]
	v_mov_b32_e32 v91, v79
	ds_read_b128 v[86:89], v152 offset:2048
	v_pk_add_f32 v[78:79], v[92:93], v[90:91]
	ds_read_b128 v[90:93], v152 offset:3072
	v_pk_add_f32 v[78:79], v[78:79], v[78:79] op_sel:[0,1] op_sel_hi:[1,0]
	s_waitcnt lgkmcnt(0)
	v_xor_b32_e32 v89, 0x80000000, v89
	v_xor_b32_e32 v88, 0x80000000, v88
	v_pk_fma_f32 v[72:73], v[72:73], v[84:85], v[86:87] op_sel_hi:[1,0,1] neg_lo:[0,0,1] neg_hi:[0,0,1]
	v_xor_b32_e32 v87, 0x80000000, v93
	v_xor_b32_e32 v86, 0x80000000, v92
	v_pk_fma_f32 v[68:69], v[68:69], v[84:85], v[90:91] op_sel_hi:[1,0,1] neg_lo:[0,0,1] neg_hi:[0,0,1]
	v_pk_fma_f32 v[74:75], v[74:75], v[84:85], v[88:89] op_sel_hi:[1,0,1]
	v_pk_fma_f32 v[70:71], v[70:71], v[84:85], v[86:87] op_sel_hi:[1,0,1]
	v_mul_f32_e32 v88, v68, v68
	v_mul_f32_e32 v89, v69, v69
	v_pk_add_f32 v[86:87], v[94:95], v[94:95] op_sel:[0,1] op_sel_hi:[1,0]
	v_mov_b32_e32 v79, v89
	v_mov_b32_e32 v87, v88
	v_pk_add_f32 v[78:79], v[86:87], v[78:79]
	v_mul_f32_e32 v86, v73, v73
	v_mul_f32_e32 v92, v70, v70
	v_pk_fma_f32 v[90:91], v[72:73], v[72:73], v[86:87] op_sel_hi:[1,1,0]
	v_mul_f32_e32 v86, v75, v75
	v_mov_b32_e32 v91, v92
	v_pk_fma_f32 v[92:93], v[74:75], v[74:75], v[86:87] op_sel_hi:[1,1,0]
	ds_read_b128 v[86:89], v152 offset:4096
	v_mul_f32_e32 v96, v71, v71
	v_mov_b32_e32 v93, v96
	v_pk_add_f32 v[90:91], v[90:91], v[92:93]
	s_nop 0
	v_pk_add_f32 v[78:79], v[78:79], v[90:91]
	ds_read_b128 v[90:93], v152 offset:5120
	s_waitcnt lgkmcnt(0)
	v_pk_fma_f32 v[64:65], v[64:65], v[84:85], v[86:87] op_sel_hi:[1,0,1] neg_lo:[0,0,1] neg_hi:[0,0,1]
	v_xor_b32_e32 v87, 0x80000000, v89
	v_xor_b32_e32 v86, 0x80000000, v88
	v_pk_fma_f32 v[66:67], v[66:67], v[84:85], v[86:87] op_sel_hi:[1,0,1]
	v_pk_mul_f32 v[88:89], v[64:65], v[64:65]
	v_pk_mul_f32 v[86:87], v[66:67], v[66:67]
	v_xor_b32_e32 v93, 0x80000000, v93
	v_pk_mov_b32 v[94:95], v[88:89], v[86:87] op_sel:[1,0]
	v_mov_b32_e32 v89, v87
	v_pk_add_f32 v[94:95], v[94:95], v[88:89]
	ds_read_b128 v[86:89], v152 offset:6144
	v_xor_b32_e32 v92, 0x80000000, v92
	v_pk_fma_f32 v[62:63], v[62:63], v[84:85], v[92:93] op_sel_hi:[1,0,1]
	v_pk_fma_f32 v[60:61], v[60:61], v[84:85], v[90:91] op_sel_hi:[1,0,1] neg_lo:[0,0,1] neg_hi:[0,0,1]
	ds_read_b128 v[90:93], v152 offset:7168
	s_waitcnt lgkmcnt(0)
	v_pk_fma_f32 v[56:57], v[56:57], v[84:85], v[86:87] op_sel_hi:[1,0,1] neg_lo:[0,0,1] neg_hi:[0,0,1]
	v_xor_b32_e32 v89, 0x80000000, v89
	v_xor_b32_e32 v88, 0x80000000, v88
	v_mul_f32_e32 v86, v56, v56
	v_pk_add_f32 v[78:79], v[78:79], v[78:79] op_sel:[0,1] op_sel_hi:[1,0]
	v_pk_fma_f32 v[58:59], v[58:59], v[84:85], v[88:89] op_sel_hi:[1,0,1]
	v_mul_f32_e32 v88, v57, v57
	v_mov_b32_e32 v79, v86
	v_pk_add_f32 v[86:87], v[94:95], v[94:95] op_sel:[0,1] op_sel_hi:[1,0]
	v_mul_f32_e32 v89, v58, v58
	v_mov_b32_e32 v87, v88
	v_pk_add_f32 v[78:79], v[78:79], v[86:87]
	v_mul_f32_e32 v86, v61, v61
	v_pk_fma_f32 v[86:87], v[60:61], v[60:61], v[86:87] op_sel_hi:[1,1,0]
	v_mul_f32_e32 v88, v63, v63
	v_mul_f32_e32 v96, v59, v59
	v_mov_b32_e32 v87, v89
	v_pk_fma_f32 v[88:89], v[62:63], v[62:63], v[88:89] op_sel_hi:[1,1,0]
	v_pk_fma_f32 v[52:53], v[52:53], v[84:85], v[90:91] op_sel_hi:[1,0,1] neg_lo:[0,0,1] neg_hi:[0,0,1]
	v_mov_b32_e32 v89, v96
	v_pk_add_f32 v[86:87], v[86:87], v[88:89]
	s_nop 0
	v_pk_add_f32 v[78:79], v[78:79], v[86:87]
	v_xor_b32_e32 v87, 0x80000000, v93
	v_xor_b32_e32 v86, 0x80000000, v92
	v_pk_fma_f32 v[54:55], v[54:55], v[84:85], v[86:87] op_sel_hi:[1,0,1]
	v_pk_mul_f32 v[92:93], v[52:53], v[52:53]
	v_pk_mul_f32 v[90:91], v[54:55], v[54:55]
	ds_read_b128 v[86:89], v152 offset:8192
	v_pk_mov_b32 v[94:95], v[92:93], v[90:91] op_sel:[1,0]
	v_mov_b32_e32 v93, v91
	v_pk_add_f32 v[94:95], v[94:95], v[92:93]
	ds_read_b128 v[90:93], v152 offset:9216
	s_waitcnt lgkmcnt(0)
	v_pk_fma_f32 v[48:49], v[48:49], v[84:85], v[86:87] op_sel_hi:[1,0,1] neg_lo:[0,0,1] neg_hi:[0,0,1]
	v_xor_b32_e32 v89, 0x80000000, v89
	v_xor_b32_e32 v88, 0x80000000, v88
	v_pk_add_f32 v[78:79], v[78:79], v[78:79] op_sel:[0,1] op_sel_hi:[1,0]
	v_xor_b32_e32 v87, 0x80000000, v93
	v_xor_b32_e32 v86, 0x80000000, v92
	v_pk_fma_f32 v[44:45], v[44:45], v[84:85], v[90:91] op_sel_hi:[1,0,1] neg_lo:[0,0,1] neg_hi:[0,0,1]
	v_pk_fma_f32 v[46:47], v[46:47], v[84:85], v[86:87] op_sel_hi:[1,0,1]
	v_mul_f32_e32 v86, v44, v44
	v_pk_fma_f32 v[50:51], v[50:51], v[84:85], v[88:89] op_sel_hi:[1,0,1]
	v_mul_f32_e32 v88, v45, v45
	v_mov_b32_e32 v79, v86
	v_pk_add_f32 v[86:87], v[94:95], v[94:95] op_sel:[0,1] op_sel_hi:[1,0]
	v_mul_f32_e32 v89, v46, v46
	v_mov_b32_e32 v87, v88
	v_pk_add_f32 v[78:79], v[78:79], v[86:87]
	v_mul_f32_e32 v86, v49, v49
	v_pk_fma_f32 v[90:91], v[48:49], v[48:49], v[86:87] op_sel_hi:[1,1,0]
	v_mul_f32_e32 v86, v51, v51
	v_mov_b32_e32 v91, v89
	v_pk_fma_f32 v[92:93], v[50:51], v[50:51], v[86:87] op_sel_hi:[1,1,0]
	ds_read_b128 v[86:89], v152 offset:10240
	v_mul_f32_e32 v96, v47, v47
	v_mov_b32_e32 v93, v96
	v_pk_add_f32 v[90:91], v[90:91], v[92:93]
	s_nop 0
	v_pk_add_f32 v[78:79], v[78:79], v[90:91]
	ds_read_b128 v[90:93], v152 offset:11264
	s_waitcnt lgkmcnt(0)
	v_pk_fma_f32 v[40:41], v[40:41], v[84:85], v[86:87] op_sel_hi:[1,0,1] neg_lo:[0,0,1] neg_hi:[0,0,1]
	v_xor_b32_e32 v87, 0x80000000, v89
	v_xor_b32_e32 v86, 0x80000000, v88
	v_pk_fma_f32 v[42:43], v[42:43], v[84:85], v[86:87] op_sel_hi:[1,0,1]
	v_pk_mul_f32 v[88:89], v[40:41], v[40:41]
	v_pk_mul_f32 v[86:87], v[42:43], v[42:43]
	v_xor_b32_e32 v93, 0x80000000, v93
	v_pk_mov_b32 v[94:95], v[88:89], v[86:87] op_sel:[1,0]
	v_mov_b32_e32 v89, v87
	v_pk_add_f32 v[94:95], v[94:95], v[88:89]
	ds_read_b128 v[86:89], v152 offset:12288
	v_xor_b32_e32 v92, 0x80000000, v92
	v_pk_fma_f32 v[38:39], v[38:39], v[84:85], v[92:93] op_sel_hi:[1,0,1]
	v_pk_fma_f32 v[36:37], v[36:37], v[84:85], v[90:91] op_sel_hi:[1,0,1] neg_lo:[0,0,1] neg_hi:[0,0,1]
	ds_read_b128 v[90:93], v152 offset:13312
	s_waitcnt lgkmcnt(0)
	v_pk_fma_f32 v[32:33], v[32:33], v[84:85], v[86:87] op_sel_hi:[1,0,1] neg_lo:[0,0,1] neg_hi:[0,0,1]
	v_xor_b32_e32 v89, 0x80000000, v89
	v_xor_b32_e32 v88, 0x80000000, v88
	v_mul_f32_e32 v86, v32, v32
	v_pk_add_f32 v[78:79], v[78:79], v[78:79] op_sel:[0,1] op_sel_hi:[1,0]
	v_pk_fma_f32 v[34:35], v[34:35], v[84:85], v[88:89] op_sel_hi:[1,0,1]
	v_mul_f32_e32 v88, v33, v33
	v_mov_b32_e32 v79, v86
	v_pk_add_f32 v[86:87], v[94:95], v[94:95] op_sel:[0,1] op_sel_hi:[1,0]
	v_mul_f32_e32 v89, v34, v34
	v_mov_b32_e32 v87, v88
	v_pk_add_f32 v[78:79], v[78:79], v[86:87]
	v_mul_f32_e32 v86, v37, v37
	v_pk_fma_f32 v[86:87], v[36:37], v[36:37], v[86:87] op_sel_hi:[1,1,0]
	v_mul_f32_e32 v88, v39, v39
	v_mul_f32_e32 v96, v35, v35
	v_mov_b32_e32 v87, v89
	v_pk_fma_f32 v[88:89], v[38:39], v[38:39], v[88:89] op_sel_hi:[1,1,0]
	v_pk_fma_f32 v[28:29], v[28:29], v[84:85], v[90:91] op_sel_hi:[1,0,1] neg_lo:[0,0,1] neg_hi:[0,0,1]
	v_mov_b32_e32 v89, v96
	v_pk_add_f32 v[86:87], v[86:87], v[88:89]
	s_nop 0
	v_pk_add_f32 v[78:79], v[78:79], v[86:87]
	v_xor_b32_e32 v87, 0x80000000, v93
	v_xor_b32_e32 v86, 0x80000000, v92
	v_pk_fma_f32 v[30:31], v[30:31], v[84:85], v[86:87] op_sel_hi:[1,0,1]
	ds_read_b128 v[86:89], v152 offset:14336
	v_pk_mul_f32 v[90:91], v[30:31], v[30:31]
	v_pk_mul_f32 v[92:93], v[28:29], v[28:29]
	v_pk_add_f32 v[78:79], v[78:79], v[78:79] op_sel:[0,1] op_sel_hi:[1,0]
	v_pk_mov_b32 v[94:95], v[92:93], v[90:91] op_sel:[1,0]
	v_mov_b32_e32 v93, v91
	v_pk_add_f32 v[94:95], v[94:95], v[92:93]
	ds_read_b128 v[90:93], v152 offset:15360
	s_waitcnt lgkmcnt(0)
	v_xor_b32_e32 v89, 0x80000000, v89
	v_xor_b32_e32 v88, 0x80000000, v88
	v_pk_fma_f32 v[26:27], v[26:27], v[84:85], v[88:89] op_sel_hi:[1,0,1]
	v_pk_fma_f32 v[24:25], v[24:25], v[84:85], v[86:87] op_sel_hi:[1,0,1] neg_lo:[0,0,1] neg_hi:[0,0,1]
	global_load_dwordx4 v[86:89], v[136:137], off
	global_load_dwordx4 v[166:169], v[136:137], off offset:64
	global_load_dwordx4 v[170:173], v[136:137], off offset:128
	global_load_dwordx4 v[174:177], v[136:137], off offset:192
	global_load_dwordx4 v[178:181], v[136:137], off offset:256
	global_load_dwordx4 v[182:185], v[136:137], off offset:320
	global_load_dwordx4 v[186:189], v[136:137], off offset:384
	global_load_dwordx4 v[190:193], v[136:137], off offset:448
	global_load_dwordx4 v[194:197], v[136:137], off offset:512
	global_load_dwordx4 v[198:201], v[136:137], off offset:576
	global_load_dwordx4 v[202:205], v[136:137], off offset:640
	global_load_dwordx4 v[206:209], v[136:137], off offset:704
	global_load_dwordx4 v[210:213], v[136:137], off offset:768
	global_load_dwordx4 v[214:217], v[136:137], off offset:832
	global_load_dwordx4 v[218:221], v[136:137], off offset:896
	global_load_dwordx4 v[222:225], v[136:137], off offset:960
	v_xor_b32_e32 v93, 0x80000000, v93
	v_xor_b32_e32 v92, 0x80000000, v92
	v_pk_fma_f32 v[20:21], v[20:21], v[84:85], v[90:91] op_sel_hi:[1,0,1] neg_lo:[0,0,1] neg_hi:[0,0,1]
	v_pk_fma_f32 v[22:23], v[22:23], v[84:85], v[92:93] op_sel_hi:[1,0,1]
	v_mul_f32_e32 v84, v20, v20
	v_mul_f32_e32 v92, v21, v21
	v_pk_add_f32 v[90:91], v[94:95], v[94:95] op_sel:[0,1] op_sel_hi:[1,0]
	v_mov_b32_e32 v79, v84
	v_mov_b32_e32 v91, v92
	v_mul_f32_e32 v84, v25, v25
	v_mul_f32_e32 v93, v22, v22
	v_pk_add_f32 v[78:79], v[78:79], v[90:91]
	v_pk_fma_f32 v[90:91], v[24:25], v[24:25], v[84:85] op_sel_hi:[1,1,0]
	v_mul_f32_e32 v84, v27, v27
	v_mul_f32_e32 v96, v23, v23
	v_mov_b32_e32 v91, v93
	v_pk_fma_f32 v[92:93], v[26:27], v[26:27], v[84:85] op_sel_hi:[1,1,0]
	s_waitcnt vmcnt(0)
	v_pk_mul_f32 v[80:81], v[80:81], v[86:87]
	v_mov_b32_e32 v93, v96
	v_pk_add_f32 v[90:91], v[90:91], v[92:93]
	v_pk_mul_f32 v[82:83], v[82:83], v[88:89]
	v_pk_add_f32 v[78:79], v[78:79], v[90:91]
	s_nop 0
	v_add_f32_e32 v78, v78, v79
	ds_bpermute_b32 v1, v1, v78
	s_waitcnt lgkmcnt(0)
	v_add_f32_e32 v1, v78, v1
	ds_bpermute_b32 v78, v85, v1
	s_waitcnt lgkmcnt(0)
	v_add_f32_e32 v1, v1, v78
	v_fmamk_f32 v1, v1, 0x3b800000, v162
	v_mul_f32_e32 v78, 0x4f800000, v1
	v_cmp_gt_f32_e32 vcc, s88, v1
	s_nop 1
	v_cndmask_b32_e32 v1, v1, v78, vcc
	v_sqrt_f32_e32 v78, v1
	s_nop 0
	v_add_u32_e32 v79, -1, v78
	v_fma_f32 v84, -v79, v78, v1
	v_cmp_ge_f32_e64 s[0:1], 0, v84
	v_add_u32_e32 v84, 1, v78
	s_nop 0
	v_cndmask_b32_e64 v79, v78, v79, s[0:1]
	v_fma_f32 v78, -v84, v78, v1
	v_cmp_lt_f32_e64 s[0:1], 0, v78
	s_nop 1
	v_cndmask_b32_e64 v78, v79, v84, s[0:1]
	v_mul_f32_e32 v79, 0x37800000, v78
	v_cndmask_b32_e32 v78, v78, v79, vcc
	v_cmp_class_f32_e32 vcc, v1, v163
	s_nop 1
	v_cndmask_b32_e32 v1, v78, v1, vcc
	v_div_scale_f32 v78, s[0:1], v1, v1, s89
	v_rcp_f32_e32 v79, v78
	s_nop 0
	v_fma_f32 v84, -v78, v79, 1.0
	v_fmac_f32_e32 v79, v84, v79
	v_div_scale_f32 v84, vcc, s89, v1, s89
	v_mul_f32_e32 v85, v84, v79
	v_fma_f32 v90, -v78, v85, v84
	v_fmac_f32_e32 v85, v90, v79
	v_fma_f32 v78, -v78, v85, v84
	v_div_fmas_f32 v78, v78, v79, v85
	v_div_fixup_f32 v84, v78, v1, s89
	v_lshrrev_b32_e32 v78, 5, v227
	v_mul_u32_u24_e32 v96, 0x210, v78
	v_add_u32_e32 v78, s91, v78
	v_mov_b32_e32 v79, v0
	v_lshlrev_b64 v[78:79], 12, v[78:79]
	v_lshl_add_u64 v[78:79], s[4:5], 0, v[78:79]
	v_lshl_add_u64 v[78:79], v[78:79], 0, s[50:51]
	v_and_b32_e32 v98, 31, v227
	v_lshlrev_b32_e32 v98, 4, v98
	v_mov_b32_e32 v99, v0
	v_add_u32_e32 v96, v96, v98
	v_lshlrev_b32_e32 v100, 4, v227
	v_sub_u32_e32 v100, v152, v100
	v_add_u32_e32 v96, v100, v96
	v_lshl_add_u64 v[78:79], v[78:79], 0, v[98:99]
	v_and_b32_e32 v97, 15, v227
	v_mul_u32_u24_e32 v97, 0x210, v97
	v_lshrrev_b32_e32 v98, 4, v227
	v_lshl_add_u32 v97, v98, 3, v97
	v_add_u32_e32 v97, v100, v97
	v_pk_mul_f32 v[80:81], v[80:81], v[84:85] op_sel_hi:[1,0]
	v_pk_mul_f32 v[82:83], v[82:83], v[84:85] op_sel_hi:[1,0]
	v_cvt_pk_bf16_f32 v80, v80, v81
	s_nop 0
	v_cvt_pk_bf16_f32 v81, v82, v83
	ds_write_b64 v97, v[80:81]
	v_pk_mul_f32 v[2:3], v[2:3], v[166:167]
	v_pk_mul_f32 v[76:77], v[76:77], v[168:169]
	v_pk_mul_f32 v[2:3], v[2:3], v[84:85] op_sel_hi:[1,0]
	v_pk_mul_f32 v[76:77], v[76:77], v[84:85] op_sel_hi:[1,0]
	v_cvt_pk_bf16_f32 v2, v2, v3
	s_nop 0
	v_cvt_pk_bf16_f32 v3, v76, v77
	ds_write_b64 v97, v[2:3] offset:32
	v_pk_mul_f32 v[2:3], v[72:73], v[170:171]
	v_pk_mul_f32 v[72:73], v[74:75], v[172:173]
	v_pk_mul_f32 v[2:3], v[2:3], v[84:85] op_sel_hi:[1,0]
	v_pk_mul_f32 v[72:73], v[72:73], v[84:85] op_sel_hi:[1,0]
	v_cvt_pk_bf16_f32 v2, v2, v3
	s_nop 0
	v_cvt_pk_bf16_f32 v3, v72, v73
	ds_write_b64 v97, v[2:3] offset:64
	v_pk_mul_f32 v[2:3], v[68:69], v[174:175]
	v_pk_mul_f32 v[68:69], v[70:71], v[176:177]
	v_pk_mul_f32 v[2:3], v[84:85], v[2:3] op_sel_hi:[0,1]
	v_pk_mul_f32 v[68:69], v[84:85], v[68:69] op_sel_hi:[0,1]
	v_cvt_pk_bf16_f32 v2, v2, v3
	v_cvt_pk_bf16_f32 v3, v68, v69
	ds_write_b64 v97, v[2:3] offset:96
	v_pk_mul_f32 v[2:3], v[64:65], v[178:179]
	v_pk_mul_f32 v[64:65], v[66:67], v[180:181]
	v_pk_mul_f32 v[2:3], v[84:85], v[2:3] op_sel_hi:[0,1]
	v_pk_mul_f32 v[64:65], v[84:85], v[64:65] op_sel_hi:[0,1]
	v_cvt_pk_bf16_f32 v2, v2, v3
	v_cvt_pk_bf16_f32 v3, v64, v65
	ds_write_b64 v97, v[2:3] offset:128
	v_pk_mul_f32 v[2:3], v[60:61], v[182:183]
	v_pk_mul_f32 v[60:61], v[62:63], v[184:185]
	v_pk_mul_f32 v[2:3], v[84:85], v[2:3] op_sel_hi:[0,1]
	v_pk_mul_f32 v[60:61], v[84:85], v[60:61] op_sel_hi:[0,1]
	v_cvt_pk_bf16_f32 v2, v2, v3
	v_cvt_pk_bf16_f32 v3, v60, v61
	ds_write_b64 v97, v[2:3] offset:160
	v_pk_mul_f32 v[2:3], v[56:57], v[186:187]
	v_pk_mul_f32 v[56:57], v[58:59], v[188:189]
	v_pk_mul_f32 v[2:3], v[84:85], v[2:3] op_sel_hi:[0,1]
	v_pk_mul_f32 v[56:57], v[84:85], v[56:57] op_sel_hi:[0,1]
	v_cvt_pk_bf16_f32 v2, v2, v3
	v_cvt_pk_bf16_f32 v3, v56, v57
	ds_write_b64 v97, v[2:3] offset:192
	v_pk_mul_f32 v[2:3], v[52:53], v[190:191]
	v_pk_mul_f32 v[52:53], v[54:55], v[192:193]
	v_pk_mul_f32 v[2:3], v[84:85], v[2:3] op_sel_hi:[0,1]
	v_pk_mul_f32 v[52:53], v[84:85], v[52:53] op_sel_hi:[0,1]
	v_cvt_pk_bf16_f32 v2, v2, v3
	v_cvt_pk_bf16_f32 v3, v52, v53
	ds_write_b64 v97, v[2:3] offset:224
	v_pk_mul_f32 v[2:3], v[48:49], v[194:195]
	v_pk_mul_f32 v[48:49], v[50:51], v[196:197]
	v_pk_mul_f32 v[2:3], v[84:85], v[2:3] op_sel_hi:[0,1]
	v_pk_mul_f32 v[48:49], v[84:85], v[48:49] op_sel_hi:[0,1]
	v_cvt_pk_bf16_f32 v2, v2, v3
	v_cvt_pk_bf16_f32 v3, v48, v49
	ds_write_b64 v97, v[2:3] offset:256
	v_pk_mul_f32 v[2:3], v[44:45], v[198:199]
	v_pk_mul_f32 v[44:45], v[46:47], v[200:201]
	v_pk_mul_f32 v[2:3], v[84:85], v[2:3] op_sel_hi:[0,1]
	v_pk_mul_f32 v[44:45], v[84:85], v[44:45] op_sel_hi:[0,1]
	v_cvt_pk_bf16_f32 v2, v2, v3
	v_cvt_pk_bf16_f32 v3, v44, v45
	ds_write_b64 v97, v[2:3] offset:288
	v_pk_mul_f32 v[2:3], v[40:41], v[202:203]
	v_pk_mul_f32 v[40:41], v[42:43], v[204:205]
	v_pk_mul_f32 v[2:3], v[84:85], v[2:3] op_sel_hi:[0,1]
	v_pk_mul_f32 v[40:41], v[84:85], v[40:41] op_sel_hi:[0,1]
	v_cvt_pk_bf16_f32 v2, v2, v3
	v_cvt_pk_bf16_f32 v3, v40, v41
	ds_write_b64 v97, v[2:3] offset:320
	v_pk_mul_f32 v[2:3], v[36:37], v[206:207]
	v_pk_mul_f32 v[36:37], v[38:39], v[208:209]
	v_pk_mul_f32 v[2:3], v[84:85], v[2:3] op_sel_hi:[0,1]
	v_pk_mul_f32 v[36:37], v[84:85], v[36:37] op_sel_hi:[0,1]
	v_cvt_pk_bf16_f32 v2, v2, v3
	v_cvt_pk_bf16_f32 v3, v36, v37
	ds_write_b64 v97, v[2:3] offset:352
	v_pk_mul_f32 v[2:3], v[32:33], v[210:211]
	v_pk_mul_f32 v[32:33], v[34:35], v[212:213]
	v_pk_mul_f32 v[2:3], v[84:85], v[2:3] op_sel_hi:[0,1]
	v_pk_mul_f32 v[32:33], v[84:85], v[32:33] op_sel_hi:[0,1]
	v_cvt_pk_bf16_f32 v2, v2, v3
	v_cvt_pk_bf16_f32 v3, v32, v33
	ds_write_b64 v97, v[2:3] offset:384
	v_pk_mul_f32 v[2:3], v[28:29], v[214:215]
	v_pk_mul_f32 v[28:29], v[30:31], v[216:217]
	v_pk_mul_f32 v[2:3], v[84:85], v[2:3] op_sel_hi:[0,1]
	v_pk_mul_f32 v[28:29], v[84:85], v[28:29] op_sel_hi:[0,1]
	v_cvt_pk_bf16_f32 v2, v2, v3
	v_cvt_pk_bf16_f32 v3, v28, v29
	ds_write_b64 v97, v[2:3] offset:416
	v_pk_mul_f32 v[2:3], v[24:25], v[218:219]
	v_pk_mul_f32 v[24:25], v[26:27], v[220:221]
	v_pk_mul_f32 v[2:3], v[84:85], v[2:3] op_sel_hi:[0,1]
	v_pk_mul_f32 v[24:25], v[84:85], v[24:25] op_sel_hi:[0,1]
	v_cvt_pk_bf16_f32 v2, v2, v3
	v_cvt_pk_bf16_f32 v3, v24, v25
	ds_write_b64 v97, v[2:3] offset:448
	v_pk_mul_f32 v[2:3], v[20:21], v[222:223]
	v_pk_mul_f32 v[20:21], v[22:23], v[224:225]
	v_pk_mul_f32 v[2:3], v[84:85], v[2:3] op_sel_hi:[0,1]
	v_pk_mul_f32 v[20:21], v[84:85], v[20:21] op_sel_hi:[0,1]
	v_cvt_pk_bf16_f32 v2, v2, v3
	v_cvt_pk_bf16_f32 v3, v20, v21
	ds_write_b64 v97, v[2:3] offset:480
	s_mov_b32 s0, 0x2000
	s_mov_b32 s1, 0
	s_waitcnt lgkmcnt(0)
	ds_read_b128 v[98:101], v96
	ds_read_b128 v[102:105], v96 offset:1056
	ds_read_b128 v[106:109], v96 offset:2112
	ds_read_b128 v[110:113], v96 offset:3168
	ds_read_b128 v[114:117], v96 offset:4224
	ds_read_b128 v[118:121], v96 offset:5280
	ds_read_b128 v[122:125], v96 offset:6336
	ds_read_b128 v[126:129], v96 offset:7392
	s_waitcnt lgkmcnt(7)
	global_store_dwordx4 v[78:79], v[98:101], off
	v_lshl_add_u64 v[78:79], v[78:79], 0, s[0:1]
	s_waitcnt lgkmcnt(6)
	global_store_dwordx4 v[78:79], v[102:105], off
	v_lshl_add_u64 v[78:79], v[78:79], 0, s[0:1]
	s_waitcnt lgkmcnt(5)
	global_store_dwordx4 v[78:79], v[106:109], off
	v_lshl_add_u64 v[78:79], v[78:79], 0, s[0:1]
	s_waitcnt lgkmcnt(4)
	global_store_dwordx4 v[78:79], v[110:113], off
	v_lshl_add_u64 v[78:79], v[78:79], 0, s[0:1]
	s_waitcnt lgkmcnt(3)
	global_store_dwordx4 v[78:79], v[114:117], off
	v_lshl_add_u64 v[78:79], v[78:79], 0, s[0:1]
	s_waitcnt lgkmcnt(2)
	global_store_dwordx4 v[78:79], v[118:121], off
	v_lshl_add_u64 v[78:79], v[78:79], 0, s[0:1]
	s_waitcnt lgkmcnt(1)
	global_store_dwordx4 v[78:79], v[122:125], off
	v_lshl_add_u64 v[78:79], v[78:79], 0, s[0:1]
	s_waitcnt lgkmcnt(0)
	global_store_dwordx4 v[78:79], v[126:129], off
	s_branch .LBB0_1115
